# tail GEMMs (G3/G4/G5): the 8 partial-sum ds_reads issued together with counted lgkmcnt waits instead of 8 serialized round trips; on top of the peeled K step
# speedup vs baseline: 1.0155x; 1.0004x over previous
.LBB0_849:
	s_and_b32 s8, s3, 0x70
	v_or_b32_e32 v2, s8, v6
	v_mov_b32_e32 v10, 0x1000000
	s_and_b32 s8, s4, 0xffffffc0
	v_lshl_or_b32 v2, v2, 10, v10
	v_or_b32_e32 v10, s8, v6
	v_ashrrev_i32_e32 v11, 31, v10
	v_lshlrev_b64 v[10:11], 11, v[10:11]
	v_lshl_add_u64 v[62:63], v[4:5], 0, v[10:11]
	s_mov_b32 s9, 0x8000
	v_add_co_u32_e32 v70, vcc, s9, v62
	s_mov_b32 s9, 0x10000
	s_nop 0
	v_addc_co_u32_e32 v71, vcc, 0, v63, vcc
	v_add_co_u32_e32 v78, vcc, s9, v62
	s_mov_b32 s9, 0x18000
	s_nop 0
	v_addc_co_u32_e32 v79, vcc, 0, v63, vcc
	v_lshlrev_b32_e32 v2, 1, v2
	v_add_co_u32_e32 v86, vcc, s9, v62
	v_lshl_add_u64 v[54:55], v[0:1], 0, v[2:3]
	s_nop 0
	v_addc_co_u32_e32 v87, vcc, 0, v63, vcc
	global_load_dwordx4 v[10:13], v[54:55], off
	global_load_dwordx4 v[14:17], v[54:55], off offset:64
	global_load_dwordx4 v[18:21], v[62:63], off
	global_load_dwordx4 v[22:25], v[62:63], off offset:64
	global_load_dwordx4 v[26:29], v[70:71], off
	global_load_dwordx4 v[30:33], v[70:71], off offset:64
	global_load_dwordx4 v[34:37], v[78:79], off
	global_load_dwordx4 v[38:41], v[78:79], off offset:64
	global_load_dwordx4 v[42:45], v[86:87], off
	global_load_dwordx4 v[46:49], v[86:87], off offset:64
	global_load_dwordx4 v[50:53], v[54:55], off offset:128
	s_nop 0
	global_load_dwordx4 v[54:57], v[54:55], off offset:192
	s_nop 0
	global_load_dwordx4 v[58:61], v[62:63], off offset:128
	s_nop 0
	global_load_dwordx4 v[62:65], v[62:63], off offset:192
	s_nop 0
	global_load_dwordx4 v[66:69], v[70:71], off offset:128
	s_nop 0
	global_load_dwordx4 v[70:73], v[70:71], off offset:192
	s_nop 0
	global_load_dwordx4 v[74:77], v[78:79], off offset:128
	s_nop 0
	global_load_dwordx4 v[78:81], v[78:79], off offset:192
	s_nop 0
	global_load_dwordx4 v[82:85], v[86:87], off offset:128
	s_nop 0
	global_load_dwordx4 v[86:89], v[86:87], off offset:192
	s_waitcnt vmcnt(0)
	v_mfma_f32_16x16x32_bf16 v[18:21], v[18:21], v[10:13], 0
	s_andn2_b64 vcc, exec, s[0:1]
	v_mfma_f32_16x16x32_bf16 v[26:29], v[26:29], v[10:13], 0
	v_mfma_f32_16x16x32_bf16 v[34:37], v[34:37], v[10:13], 0
	v_mfma_f32_16x16x32_bf16 v[10:13], v[42:45], v[10:13], 0
	v_mfma_f32_16x16x32_bf16 v[18:21], v[22:25], v[14:17], v[18:21]
	v_mfma_f32_16x16x32_bf16 v[10:13], v[46:49], v[14:17], v[10:13]
	v_mfma_f32_16x16x32_bf16 v[22:25], v[30:33], v[14:17], v[26:29]
	v_mfma_f32_16x16x32_bf16 v[26:29], v[38:41], v[14:17], v[34:37]
	v_mfma_f32_16x16x32_bf16 v[14:17], v[58:61], v[50:53], v[18:21]
	v_mfma_f32_16x16x32_bf16 v[10:13], v[82:85], v[50:53], v[10:13]
	v_mfma_f32_16x16x32_bf16 v[18:21], v[66:69], v[50:53], v[22:25]
	v_mfma_f32_16x16x32_bf16 v[22:25], v[74:77], v[50:53], v[26:29]
	v_mfma_f32_16x16x32_bf16 v[14:17], v[62:65], v[54:57], v[14:17]
	s_nop 2
	v_add_u32_e32 v26, s2, v7
	v_mfma_f32_16x16x32_bf16 v[10:13], v[86:89], v[54:57], v[10:13]
	v_mfma_f32_16x16x32_bf16 v[18:21], v[70:73], v[54:57], v[18:21]
	v_mfma_f32_16x16x32_bf16 v[22:25], v[78:81], v[54:57], v[22:25]
	s_nop 0
	ds_write_b128 v26, v[14:17]
	s_nop 4
	ds_write_b128 v26, v[18:21] offset:1024
	ds_write_b128 v26, v[22:25] offset:2048
	ds_write_b128 v26, v[10:13] offset:3072
	s_waitcnt lgkmcnt(0)
	s_barrier
	s_cbranch_vccnz .LBB0_848
	ds_read_b128 v[10:13], v8
	ds_read_b128 v[14:17], v8 offset:4096
	ds_read_b128 v[32:35], v8 offset:8192
	ds_read_b128 v[36:39], v8 offset:12288
	ds_read_b128 v[40:43], v8 offset:16384
	ds_read_b128 v[44:47], v8 offset:20480
	ds_read_b128 v[48:51], v8 offset:24576
	ds_read_b128 v[52:55], v8 offset:28672
	s_waitcnt lgkmcnt(6)
	v_pk_add_f32 v[16:17], v[12:13], v[16:17]
	v_pk_add_f32 v[14:15], v[10:11], v[14:15]
	s_waitcnt lgkmcnt(5)
	v_pk_add_f32 v[16:17], v[16:17], v[34:35]
	v_pk_add_f32 v[14:15], v[14:15], v[32:33]
	s_waitcnt lgkmcnt(4)
	v_pk_add_f32 v[16:17], v[16:17], v[38:39]
	v_pk_add_f32 v[14:15], v[14:15], v[36:37]
	s_waitcnt lgkmcnt(3)
	v_pk_add_f32 v[16:17], v[16:17], v[42:43]
	v_pk_add_f32 v[14:15], v[14:15], v[40:41]
	s_waitcnt lgkmcnt(2)
	v_pk_add_f32 v[16:17], v[16:17], v[46:47]
	v_pk_add_f32 v[14:15], v[14:15], v[44:45]
	s_waitcnt lgkmcnt(1)
	v_pk_add_f32 v[16:17], v[16:17], v[50:51]
	v_pk_add_f32 v[14:15], v[14:15], v[48:49]
	s_waitcnt lgkmcnt(0)
	v_pk_add_f32 v[10:11], v[14:15], v[52:53]
	v_add_u32_e32 v14, s8, v9
	v_pk_add_f32 v[12:13], v[16:17], v[54:55]
	v_lshl_add_u64 v[16:17], s[82:83], 0, v[2:3]
	v_ashrrev_i32_e32 v15, 31, v14
	v_lshl_add_u64 v[14:15], v[14:15], 1, v[16:17]
	v_cvt_pk_bf16_f32 v10, v10, v11
	v_cvt_pk_bf16_f32 v11, v12, v13
	global_store_dwordx2 v[14:15], v[10:11], off
	s_branch .LBB0_848

.LBB0_1107:
	s_and_b32 s10, s5, 0x70
	v_or_b32_e32 v11, s10, v10
	s_and_b32 s10, s8, 0xffffffc0
	v_or_b32_e32 v12, s10, v6
	v_ashrrev_i32_e32 v13, 31, v12
	v_lshlrev_b64 v[12:13], 11, v[12:13]
	v_lshl_add_u64 v[64:65], v[4:5], 0, v[12:13]
	s_mov_b32 s11, 0x8000
	v_add_co_u32_e32 v72, vcc, s11, v64
	s_mov_b32 s11, 0x10000
	s_nop 0
	v_addc_co_u32_e32 v73, vcc, 0, v65, vcc
	v_add_co_u32_e32 v80, vcc, s11, v64
	s_mov_b32 s11, 0x18000
	s_nop 0
	v_addc_co_u32_e32 v81, vcc, 0, v65, vcc
	v_lshlrev_b32_e32 v2, 11, v11
	v_add_co_u32_e32 v88, vcc, s11, v64
	v_lshl_add_u64 v[56:57], v[0:1], 0, v[2:3]
	s_nop 0
	v_addc_co_u32_e32 v89, vcc, 0, v65, vcc
	global_load_dwordx4 v[12:15], v[56:57], off
	global_load_dwordx4 v[16:19], v[56:57], off offset:64
	global_load_dwordx4 v[20:23], v[64:65], off
	global_load_dwordx4 v[24:27], v[64:65], off offset:64
	global_load_dwordx4 v[28:31], v[72:73], off
	global_load_dwordx4 v[32:35], v[72:73], off offset:64
	global_load_dwordx4 v[36:39], v[80:81], off
	global_load_dwordx4 v[40:43], v[80:81], off offset:64
	global_load_dwordx4 v[44:47], v[88:89], off
	global_load_dwordx4 v[48:51], v[88:89], off offset:64
	global_load_dwordx4 v[52:55], v[56:57], off offset:128
	s_nop 0
	global_load_dwordx4 v[56:59], v[56:57], off offset:192
	s_nop 0
	global_load_dwordx4 v[60:63], v[64:65], off offset:128
	s_nop 0
	global_load_dwordx4 v[64:67], v[64:65], off offset:192
	s_nop 0
	global_load_dwordx4 v[68:71], v[72:73], off offset:128
	s_nop 0
	global_load_dwordx4 v[72:75], v[72:73], off offset:192
	s_nop 0
	global_load_dwordx4 v[76:79], v[80:81], off offset:128
	s_nop 0
	global_load_dwordx4 v[80:83], v[80:81], off offset:192
	s_nop 0
	global_load_dwordx4 v[84:87], v[88:89], off offset:128
	s_nop 0
	global_load_dwordx4 v[88:91], v[88:89], off offset:192
	s_waitcnt vmcnt(0)
	v_mfma_f32_16x16x32_bf16 v[20:23], v[20:23], v[12:15], 0
	v_add_u32_e32 v2, s4, v7
	s_andn2_b64 vcc, exec, s[2:3]
	v_mfma_f32_16x16x32_bf16 v[28:31], v[28:31], v[12:15], 0
	v_mfma_f32_16x16x32_bf16 v[36:39], v[36:39], v[12:15], 0
	v_mfma_f32_16x16x32_bf16 v[12:15], v[44:47], v[12:15], 0
	v_mfma_f32_16x16x32_bf16 v[20:23], v[24:27], v[16:19], v[20:23]
	v_mfma_f32_16x16x32_bf16 v[12:15], v[48:51], v[16:19], v[12:15]
	v_mfma_f32_16x16x32_bf16 v[24:27], v[32:35], v[16:19], v[28:31]
	v_mfma_f32_16x16x32_bf16 v[28:31], v[40:43], v[16:19], v[36:39]
	v_mfma_f32_16x16x32_bf16 v[16:19], v[60:63], v[52:55], v[20:23]
	v_mfma_f32_16x16x32_bf16 v[12:15], v[84:87], v[52:55], v[12:15]
	v_mfma_f32_16x16x32_bf16 v[20:23], v[68:71], v[52:55], v[24:27]
	v_mfma_f32_16x16x32_bf16 v[24:27], v[76:79], v[52:55], v[28:31]
	v_mfma_f32_16x16x32_bf16 v[16:19], v[64:67], v[56:59], v[16:19]
	v_mfma_f32_16x16x32_bf16 v[12:15], v[88:91], v[56:59], v[12:15]
	v_mfma_f32_16x16x32_bf16 v[20:23], v[72:75], v[56:59], v[20:23]
	v_mfma_f32_16x16x32_bf16 v[24:27], v[80:83], v[56:59], v[24:27]
	s_nop 4
	ds_write_b128 v2, v[16:19]
	s_nop 0
	ds_write_b128 v2, v[20:23] offset:1024
	ds_write_b128 v2, v[24:27] offset:2048
	ds_write_b128 v2, v[12:15] offset:3072
	s_waitcnt lgkmcnt(0)
	s_barrier
	s_cbranch_vccnz .LBB0_1106
	v_lshlrev_b32_e32 v2, 2, v11
	ds_read_b128 v[12:15], v8
	ds_read_b128 v[16:19], v8 offset:4096
	ds_read_b128 v[32:35], v8 offset:8192
	ds_read_b128 v[36:39], v8 offset:12288
	ds_read_b128 v[40:43], v8 offset:16384
	ds_read_b128 v[44:47], v8 offset:20480
	ds_read_b128 v[48:51], v8 offset:24576
	ds_read_b128 v[52:55], v8 offset:28672
	global_load_dword v2, v2, s[70:71]
	s_waitcnt lgkmcnt(6)
	v_pk_add_f32 v[18:19], v[14:15], v[18:19]
	v_pk_add_f32 v[16:17], v[12:13], v[16:17]
	s_waitcnt lgkmcnt(5)
	v_pk_add_f32 v[18:19], v[18:19], v[34:35]
	v_pk_add_f32 v[16:17], v[16:17], v[32:33]
	s_waitcnt lgkmcnt(4)
	v_pk_add_f32 v[18:19], v[18:19], v[38:39]
	v_pk_add_f32 v[16:17], v[16:17], v[36:37]
	s_waitcnt lgkmcnt(3)
	v_pk_add_f32 v[18:19], v[18:19], v[42:43]
	v_pk_add_f32 v[16:17], v[16:17], v[40:41]
	s_waitcnt lgkmcnt(2)
	v_pk_add_f32 v[18:19], v[18:19], v[46:47]
	v_pk_add_f32 v[16:17], v[16:17], v[44:45]
	s_waitcnt lgkmcnt(1)
	v_pk_add_f32 v[18:19], v[18:19], v[50:51]
	v_pk_add_f32 v[16:17], v[16:17], v[48:49]
	s_waitcnt lgkmcnt(0)
	v_pk_add_f32 v[14:15], v[18:19], v[54:55]
	v_pk_add_f32 v[12:13], v[16:17], v[52:53]
	v_add_u32_e32 v16, s10, v9
	v_ashrrev_i32_e32 v17, 31, v16
	s_waitcnt vmcnt(0)
	v_mul_f32_e32 v12, v2, v12
	v_mul_f32_e32 v13, v2, v13
	v_mul_f32_e32 v14, v2, v14
	v_mul_f32_e32 v2, v2, v15
	v_max_f32_e32 v12, 0, v12
	v_max_f32_e32 v13, 0, v13
	v_max_f32_e32 v14, 0, v14
	v_max_f32_e32 v15, 0, v2
	v_lshlrev_b32_e32 v2, 13, v11
	v_pk_mul_f32 v[12:13], v[12:13], v[12:13]
	v_pk_mul_f32 v[14:15], v[14:15], v[14:15]
	v_lshl_add_u64 v[18:19], s[94:95], 0, v[2:3]
	v_lshl_add_u64 v[16:17], v[16:17], 1, v[18:19]
	v_cvt_pk_bf16_f32 v12, v12, v13
	v_cvt_pk_bf16_f32 v13, v14, v15
	global_store_dwordx2 v[16:17], v[12:13], off
	s_branch .LBB0_1106

.LBB0_1184:
	s_and_b32 s10, s5, 0x70
	v_or_b32_e32 v21, s10, v20
	s_and_b32 s10, s8, 0xffffffc0
	v_or_b32_e32 v6, s10, v16
	v_ashrrev_i32_e32 v7, 31, v6
	v_lshlrev_b64 v[6:7], 13, v[6:7]
	v_lshl_add_u64 v[6:7], v[4:5], 0, v[6:7]
	v_add_co_u32_e32 v8, vcc, s16, v6
	v_lshlrev_b32_e32 v2, 13, v21
	s_nop 0
	v_addc_co_u32_e32 v9, vcc, 0, v7, vcc
	v_add_co_u32_e32 v12, vcc, s17, v6
	s_mov_b32 s11, 0x60000
	s_nop 0
	v_addc_co_u32_e32 v13, vcc, 0, v7, vcc
	v_lshl_add_u64 v[10:11], v[0:1], 0, v[2:3]
	v_add_co_u32_e32 v14, vcc, s11, v6
	s_nop 1
	v_addc_co_u32_e32 v15, vcc, 0, v7, vcc
	global_load_dwordx4 v[22:25], v[10:11], off
	global_load_dwordx4 v[26:29], v[10:11], off offset:64
	global_load_dwordx4 v[30:33], v[6:7], off
	global_load_dwordx4 v[34:37], v[6:7], off offset:64
	global_load_dwordx4 v[38:41], v[8:9], off
	global_load_dwordx4 v[42:45], v[8:9], off offset:64
	global_load_dwordx4 v[46:49], v[12:13], off
	global_load_dwordx4 v[50:53], v[12:13], off offset:64
	global_load_dwordx4 v[54:57], v[14:15], off
	global_load_dwordx4 v[58:61], v[14:15], off offset:64
	global_load_dwordx4 v[62:65], v[10:11], off offset:128
	global_load_dwordx4 v[66:69], v[10:11], off offset:192
	global_load_dwordx4 v[70:73], v[6:7], off offset:128
	global_load_dwordx4 v[74:77], v[6:7], off offset:192
	global_load_dwordx4 v[78:81], v[8:9], off offset:128
	global_load_dwordx4 v[82:85], v[8:9], off offset:192
	global_load_dwordx4 v[86:89], v[12:13], off offset:128
	global_load_dwordx4 v[90:93], v[12:13], off offset:192
	global_load_dwordx4 v[94:97], v[14:15], off offset:128
	global_load_dwordx4 v[98:101], v[14:15], off offset:192
	s_waitcnt vmcnt(0)
	v_mfma_f32_16x16x32_bf16 v[30:33], v[30:33], v[22:25], 0
	v_mfma_f32_16x16x32_bf16 v[38:41], v[38:41], v[22:25], 0
	v_mfma_f32_16x16x32_bf16 v[46:49], v[46:49], v[22:25], 0
	v_mfma_f32_16x16x32_bf16 v[22:25], v[54:57], v[22:25], 0
	v_mfma_f32_16x16x32_bf16 v[30:33], v[34:37], v[26:29], v[30:33]
	v_mfma_f32_16x16x32_bf16 v[34:37], v[42:45], v[26:29], v[38:41]
	v_mfma_f32_16x16x32_bf16 v[38:41], v[50:53], v[26:29], v[46:49]
	v_mfma_f32_16x16x32_bf16 v[22:25], v[58:61], v[26:29], v[22:25]
	v_mfma_f32_16x16x32_bf16 v[26:29], v[70:73], v[62:65], v[30:33]
	v_mfma_f32_16x16x32_bf16 v[30:33], v[78:81], v[62:65], v[34:37]
	v_mfma_f32_16x16x32_bf16 v[34:37], v[86:89], v[62:65], v[38:41]
	v_mfma_f32_16x16x32_bf16 v[22:25], v[94:97], v[62:65], v[22:25]
	v_mfma_f32_16x16x32_bf16 v[26:29], v[74:77], v[66:69], v[26:29]
	v_mfma_f32_16x16x32_bf16 v[30:33], v[82:85], v[66:69], v[30:33]
	v_mfma_f32_16x16x32_bf16 v[34:37], v[90:93], v[66:69], v[34:37]
	v_mfma_f32_16x16x32_bf16 v[22:25], v[98:101], v[66:69], v[22:25]
	global_load_dwordx4 v[38:41], v[10:11], off offset:256
	global_load_dwordx4 v[42:45], v[6:7], off offset:256
	global_load_dwordx4 v[46:49], v[8:9], off offset:256
	global_load_dwordx4 v[50:53], v[12:13], off offset:256
	global_load_dwordx4 v[54:57], v[14:15], off offset:256
	global_load_dwordx4 v[58:61], v[10:11], off offset:320
	global_load_dwordx4 v[62:65], v[6:7], off offset:320
	global_load_dwordx4 v[66:69], v[8:9], off offset:320
	global_load_dwordx4 v[70:73], v[12:13], off offset:320
	global_load_dwordx4 v[74:77], v[14:15], off offset:320
	global_load_dwordx4 v[78:81], v[10:11], off offset:384
	global_load_dwordx4 v[82:85], v[6:7], off offset:384
	global_load_dwordx4 v[86:89], v[8:9], off offset:384
	global_load_dwordx4 v[90:93], v[12:13], off offset:384
	global_load_dwordx4 v[94:97], v[14:15], off offset:384
	global_load_dwordx4 v[98:101], v[10:11], off offset:448
	global_load_dwordx4 v[102:105], v[6:7], off offset:448
	global_load_dwordx4 v[106:109], v[8:9], off offset:448
	global_load_dwordx4 v[110:113], v[12:13], off offset:448
	global_load_dwordx4 v[114:117], v[14:15], off offset:448
	s_waitcnt vmcnt(0)
	v_mfma_f32_16x16x32_bf16 v[26:29], v[42:45], v[38:41], v[26:29]
	v_mfma_f32_16x16x32_bf16 v[30:33], v[46:49], v[38:41], v[30:33]
	v_mfma_f32_16x16x32_bf16 v[34:37], v[50:53], v[38:41], v[34:37]
	v_mfma_f32_16x16x32_bf16 v[22:25], v[54:57], v[38:41], v[22:25]
	v_mfma_f32_16x16x32_bf16 v[26:29], v[62:65], v[58:61], v[26:29]
	v_mfma_f32_16x16x32_bf16 v[30:33], v[66:69], v[58:61], v[30:33]
	v_mfma_f32_16x16x32_bf16 v[34:37], v[70:73], v[58:61], v[34:37]
	v_mfma_f32_16x16x32_bf16 v[22:25], v[74:77], v[58:61], v[22:25]
	v_mfma_f32_16x16x32_bf16 v[26:29], v[82:85], v[78:81], v[26:29]
	v_mfma_f32_16x16x32_bf16 v[30:33], v[86:89], v[78:81], v[30:33]
	v_mfma_f32_16x16x32_bf16 v[34:37], v[90:93], v[78:81], v[34:37]
	v_mfma_f32_16x16x32_bf16 v[22:25], v[94:97], v[78:81], v[22:25]
	v_mfma_f32_16x16x32_bf16 v[26:29], v[102:105], v[98:101], v[26:29]
	v_mfma_f32_16x16x32_bf16 v[30:33], v[106:109], v[98:101], v[30:33]
	v_mfma_f32_16x16x32_bf16 v[34:37], v[110:113], v[98:101], v[34:37]
	v_mfma_f32_16x16x32_bf16 v[22:25], v[114:117], v[98:101], v[22:25]
	global_load_dwordx4 v[38:41], v[10:11], off offset:512
	global_load_dwordx4 v[42:45], v[6:7], off offset:512
	global_load_dwordx4 v[46:49], v[8:9], off offset:512
	global_load_dwordx4 v[50:53], v[12:13], off offset:512
	global_load_dwordx4 v[54:57], v[14:15], off offset:512
	global_load_dwordx4 v[58:61], v[10:11], off offset:576
	global_load_dwordx4 v[62:65], v[6:7], off offset:576
	global_load_dwordx4 v[66:69], v[8:9], off offset:576
	global_load_dwordx4 v[70:73], v[12:13], off offset:576
	global_load_dwordx4 v[74:77], v[14:15], off offset:576
	global_load_dwordx4 v[78:81], v[10:11], off offset:640
	global_load_dwordx4 v[82:85], v[6:7], off offset:640
	global_load_dwordx4 v[86:89], v[8:9], off offset:640
	global_load_dwordx4 v[90:93], v[12:13], off offset:640
	global_load_dwordx4 v[94:97], v[14:15], off offset:640
	global_load_dwordx4 v[98:101], v[10:11], off offset:704
	global_load_dwordx4 v[102:105], v[6:7], off offset:704
	global_load_dwordx4 v[106:109], v[8:9], off offset:704
	global_load_dwordx4 v[110:113], v[12:13], off offset:704
	global_load_dwordx4 v[114:117], v[14:15], off offset:704
	s_waitcnt vmcnt(0)
	v_mfma_f32_16x16x32_bf16 v[26:29], v[42:45], v[38:41], v[26:29]
	v_mfma_f32_16x16x32_bf16 v[30:33], v[46:49], v[38:41], v[30:33]
	v_mfma_f32_16x16x32_bf16 v[34:37], v[50:53], v[38:41], v[34:37]
	v_mfma_f32_16x16x32_bf16 v[22:25], v[54:57], v[38:41], v[22:25]
	global_load_dwordx4 v[38:41], v[10:11], off offset:768
	global_load_dwordx4 v[42:45], v[10:11], off offset:832
	global_load_dwordx4 v[46:49], v[6:7], off offset:768
	global_load_dwordx4 v[50:53], v[6:7], off offset:832
	v_mfma_f32_16x16x32_bf16 v[26:29], v[62:65], v[58:61], v[26:29]
	v_mfma_f32_16x16x32_bf16 v[30:33], v[66:69], v[58:61], v[30:33]
	v_mfma_f32_16x16x32_bf16 v[34:37], v[70:73], v[58:61], v[34:37]
	v_mfma_f32_16x16x32_bf16 v[22:25], v[74:77], v[58:61], v[22:25]
	global_load_dwordx4 v[54:57], v[8:9], off offset:768
	global_load_dwordx4 v[58:61], v[8:9], off offset:832
	global_load_dwordx4 v[62:65], v[12:13], off offset:768
	global_load_dwordx4 v[66:69], v[12:13], off offset:832
	v_mfma_f32_16x16x32_bf16 v[26:29], v[82:85], v[78:81], v[26:29]
	v_mfma_f32_16x16x32_bf16 v[30:33], v[86:89], v[78:81], v[30:33]
	v_mfma_f32_16x16x32_bf16 v[34:37], v[90:93], v[78:81], v[34:37]
	v_mfma_f32_16x16x32_bf16 v[22:25], v[94:97], v[78:81], v[22:25]
	global_load_dwordx4 v[70:73], v[14:15], off offset:768
	global_load_dwordx4 v[74:77], v[14:15], off offset:832
	global_load_dwordx4 v[78:81], v[10:11], off offset:896
	global_load_dwordx4 v[82:85], v[10:11], off offset:960
	global_load_dwordx4 v[86:89], v[6:7], off offset:896
	global_load_dwordx4 v[90:93], v[6:7], off offset:960
	global_load_dwordx4 v[94:97], v[8:9], off offset:896
	s_nop 0
	global_load_dwordx4 v[6:9], v[8:9], off offset:960
	v_mfma_f32_16x16x32_bf16 v[26:29], v[102:105], v[98:101], v[26:29]
	v_mfma_f32_16x16x32_bf16 v[30:33], v[106:109], v[98:101], v[30:33]
	v_mfma_f32_16x16x32_bf16 v[34:37], v[110:113], v[98:101], v[34:37]
	global_load_dwordx4 v[102:105], v[12:13], off offset:896
	s_nop 0
	global_load_dwordx4 v[10:13], v[12:13], off offset:960
	s_nop 0
	global_load_dwordx4 v[106:109], v[14:15], off offset:896
	global_load_dwordx4 v[110:113], v[14:15], off offset:960
	v_mfma_f32_16x16x32_bf16 v[22:25], v[114:117], v[98:101], v[22:25]
	s_waitcnt vmcnt(0)
	v_mfma_f32_16x16x32_bf16 v[26:29], v[46:49], v[38:41], v[26:29]
	v_add_u32_e32 v2, s4, v17
	s_andn2_b64 vcc, exec, s[2:3]
	v_mfma_f32_16x16x32_bf16 v[30:33], v[54:57], v[38:41], v[30:33]
	v_mfma_f32_16x16x32_bf16 v[34:37], v[62:65], v[38:41], v[34:37]
	v_mfma_f32_16x16x32_bf16 v[22:25], v[70:73], v[38:41], v[22:25]
	v_mfma_f32_16x16x32_bf16 v[26:29], v[50:53], v[42:45], v[26:29]
	v_mfma_f32_16x16x32_bf16 v[30:33], v[58:61], v[42:45], v[30:33]
	v_mfma_f32_16x16x32_bf16 v[34:37], v[66:69], v[42:45], v[34:37]
	v_mfma_f32_16x16x32_bf16 v[22:25], v[74:77], v[42:45], v[22:25]
	v_mfma_f32_16x16x32_bf16 v[26:29], v[86:89], v[78:81], v[26:29]
	v_mfma_f32_16x16x32_bf16 v[30:33], v[94:97], v[78:81], v[30:33]
	v_mfma_f32_16x16x32_bf16 v[34:37], v[102:105], v[78:81], v[34:37]
	v_mfma_f32_16x16x32_bf16 v[22:25], v[106:109], v[78:81], v[22:25]
	v_mfma_f32_16x16x32_bf16 v[26:29], v[90:93], v[82:85], v[26:29]
	v_mfma_f32_16x16x32_bf16 v[6:9], v[6:9], v[82:85], v[30:33]
	v_mfma_f32_16x16x32_bf16 v[10:13], v[10:13], v[82:85], v[34:37]
	s_nop 5
	ds_write_b128 v2, v[26:29]
	ds_write_b128 v2, v[6:9] offset:1024
	ds_write_b128 v2, v[10:13] offset:2048
	v_mfma_f32_16x16x32_bf16 v[6:9], v[110:113], v[82:85], v[22:25]
	s_nop 7
	ds_write_b128 v2, v[6:9] offset:3072
	s_waitcnt lgkmcnt(0)
	s_barrier
	s_cbranch_vccnz .LBB0_1183
	ds_read_b128 v[6:9], v18
	ds_read_b128 v[10:13], v18 offset:4096
	ds_read_b128 v[32:35], v18 offset:8192
	ds_read_b128 v[36:39], v18 offset:12288
	ds_read_b128 v[40:43], v18 offset:16384
	ds_read_b128 v[44:47], v18 offset:20480
	ds_read_b128 v[48:51], v18 offset:24576
	ds_read_b128 v[52:55], v18 offset:28672
	v_lshlrev_b32_e32 v2, 11, v21
	s_waitcnt lgkmcnt(6)
	v_pk_add_f32 v[12:13], v[8:9], v[12:13]
	v_pk_add_f32 v[10:11], v[6:7], v[10:11]
	s_waitcnt lgkmcnt(5)
	v_pk_add_f32 v[12:13], v[12:13], v[34:35]
	v_pk_add_f32 v[10:11], v[10:11], v[32:33]
	s_waitcnt lgkmcnt(4)
	v_pk_add_f32 v[12:13], v[12:13], v[38:39]
	v_pk_add_f32 v[10:11], v[10:11], v[36:37]
	s_waitcnt lgkmcnt(3)
	v_pk_add_f32 v[12:13], v[12:13], v[42:43]
	v_pk_add_f32 v[10:11], v[10:11], v[40:41]
	s_waitcnt lgkmcnt(2)
	v_pk_add_f32 v[12:13], v[12:13], v[46:47]
	v_pk_add_f32 v[10:11], v[10:11], v[44:45]
	s_waitcnt lgkmcnt(1)
	v_pk_add_f32 v[12:13], v[12:13], v[50:51]
	v_pk_add_f32 v[10:11], v[10:11], v[48:49]
	s_waitcnt lgkmcnt(0)
	v_pk_add_f32 v[6:7], v[10:11], v[52:53]
	v_add_u32_e32 v10, s10, v19
	v_pk_add_f32 v[8:9], v[12:13], v[54:55]
	v_lshl_add_u64 v[12:13], s[82:83], 0, v[2:3]
	v_ashrrev_i32_e32 v11, 31, v10
	v_lshl_add_u64 v[10:11], v[10:11], 1, v[12:13]
	v_cvt_pk_bf16_f32 v6, v6, v7
	v_cvt_pk_bf16_f32 v7, v8, v9
	global_store_dwordx2 v[10:11], v[6:7], off
	s_branch .LBB0_1183
